# grid barrier: follower workgroups issue the acquire invalidate before polling the generation word (overlaps the wait)
# speedup vs baseline: 1.0045x; 1.0045x over previous
.LBB0_88:
	s_or_b64 exec, exec, s[14:15]
	v_cvt_f32_u32_e32 v6, v4
	s_waitcnt vmcnt(0)
	v_readfirstlane_b32 s12, v5
	v_sub_u32_e32 v5, 0, v4
	v_rcp_iflag_f32_e32 v6, v6
	v_add_u32_e32 v7, s12, v3
	v_mul_f32_e32 v6, 0x4f7ffffe, v6
	v_cvt_u32_f32_e32 v6, v6
	v_mul_lo_u32 v3, v5, v6
	v_mul_hi_u32 v3, v6, v3
	v_add_u32_e32 v3, v6, v3
	v_mul_hi_u32 v3, v7, v3
	v_mul_lo_u32 v5, v3, v4
	v_sub_u32_e32 v5, v7, v5
	v_add_u32_e32 v6, 1, v3
	v_cmp_ge_u32_e32 vcc, v5, v4
	s_nop 1
	v_cndmask_b32_e32 v3, v3, v6, vcc
	v_sub_u32_e32 v6, v5, v4
	v_cndmask_b32_e32 v5, v5, v6, vcc
	v_add_u32_e32 v6, 1, v3
	v_cmp_ge_u32_e32 vcc, v5, v4
	v_add_u32_e32 v5, 1, v7
	s_nop 0
	v_cndmask_b32_e32 v3, v3, v6, vcc
	v_mul_lo_u32 v6, v4, v3
	v_add_u32_e32 v4, v6, v4
	v_cmp_ne_u32_e32 vcc, v5, v4
	s_and_saveexec_b64 s[12:13], vcc
	s_xor_b64 s[12:13], exec, s[12:13]
	s_cbranch_execz .LBB0_102
	s_waitcnt lgkmcnt(0)
	v_mov_b32_e32 v2, 0x2000
	buffer_inv sc1
	global_load_dword v2, v2, s[10:11] offset:1024 sc1
	s_add_u32 s18, s10, 0x2400
	s_addc_u32 s19, s11, 0
	s_waitcnt vmcnt(0)
	v_cmp_eq_u32_e32 vcc, v2, v3
	s_and_saveexec_b64 s[14:15], vcc
	s_cbranch_execz .LBB0_101
	s_add_u32 s16, s66, 0x1bc0200
	s_addc_u32 s17, s67, 0
	s_mov_b32 s30, 1
	s_mov_b64 s[20:21], 0
	v_mov_b32_e32 v2, 0
	s_branch .LBB0_92

.LBB0_101:
	s_or_b64 exec, exec, s[14:15]
	s_waitcnt vmcnt(0)
	s_waitcnt vmcnt(0)
.LBB0_102:
	s_andn2_saveexec_b64 s[12:13], s[12:13]
	s_cbranch_execz .LBB0_122
	s_mov_b64 s[12:13], exec
	buffer_wbl2 sc1
	buffer_inv sc1
	s_waitcnt lgkmcnt(0)
	s_waitcnt vmcnt(0)
	v_mbcnt_lo_u32_b32 v3, s12, 0
	v_mbcnt_hi_u32_b32 v3, s13, v3
	v_cmp_eq_u32_e32 vcc, 0, v3
	s_and_saveexec_b64 s[14:15], vcc
	s_cbranch_execz .LBB0_105
	s_bcnt1_i32_b64 s12, s[12:13]
	v_mov_b32_e32 v4, 0x1bc3000
	v_mov_b32_e32 v5, s12
	global_atomic_add v4, v4, v5, s[66:67] offset:1024 sc0

.LBB0_119:
	s_or_b64 exec, exec, s[12:13]
	s_mov_b64 s[12:13], exec
	v_mbcnt_lo_u32_b32 v2, s12, 0
	v_mbcnt_hi_u32_b32 v2, s13, v2
	v_cmp_eq_u32_e32 vcc, 0, v2
	s_waitcnt vmcnt(0)
	s_and_saveexec_b64 s[14:15], vcc
	s_cbranch_execz .LBB0_121
	s_bcnt1_i32_b64 s12, s[12:13]
	v_mov_b32_e32 v2, 0x2000
	v_mov_b32_e32 v3, s12
	global_atomic_add v2, v3, s[10:11] offset:1024

.LBB0_530:
	s_or_b64 exec, exec, s[12:13]
	v_cvt_f32_u32_e32 v6, v4
	s_waitcnt vmcnt(0)
	v_readfirstlane_b32 s10, v5
	v_sub_u32_e32 v5, 0, v4
	v_rcp_iflag_f32_e32 v6, v6
	v_add_u32_e32 v7, s10, v3
	v_mul_f32_e32 v6, 0x4f7ffffe, v6
	v_cvt_u32_f32_e32 v6, v6
	v_mul_lo_u32 v3, v5, v6
	v_mul_hi_u32 v3, v6, v3
	v_add_u32_e32 v3, v6, v3
	v_mul_hi_u32 v3, v7, v3
	v_mul_lo_u32 v5, v3, v4
	v_sub_u32_e32 v5, v7, v5
	v_add_u32_e32 v6, 1, v3
	v_cmp_ge_u32_e32 vcc, v5, v4
	s_nop 1
	v_cndmask_b32_e32 v3, v3, v6, vcc
	v_sub_u32_e32 v6, v5, v4
	v_cndmask_b32_e32 v5, v5, v6, vcc
	v_add_u32_e32 v6, 1, v3
	v_cmp_ge_u32_e32 vcc, v5, v4
	v_add_u32_e32 v5, 1, v7
	s_nop 0
	v_cndmask_b32_e32 v3, v3, v6, vcc
	v_mul_lo_u32 v6, v4, v3
	v_add_u32_e32 v4, v6, v4
	v_cmp_ne_u32_e32 vcc, v5, v4
	s_and_saveexec_b64 s[10:11], vcc
	s_xor_b64 s[10:11], exec, s[10:11]
	s_cbranch_execz .LBB0_544
	s_waitcnt lgkmcnt(0)
	v_mov_b32_e32 v2, 0x2000
	buffer_inv sc1
	global_load_dword v2, v2, s[8:9] offset:1024 sc1
	s_add_u32 s16, s8, 0x2400
	s_addc_u32 s17, s9, 0
	s_waitcnt vmcnt(0)
	v_cmp_eq_u32_e32 vcc, v2, v3
	s_and_saveexec_b64 s[12:13], vcc
	s_cbranch_execz .LBB0_543
	s_add_u32 s14, s66, 0x1bc0200
	s_addc_u32 s15, s67, 0
	s_mov_b32 s28, 1
	s_mov_b64 s[18:19], 0
	v_mov_b32_e32 v2, 0
	s_branch .LBB0_534

.LBB0_543:
	s_or_b64 exec, exec, s[12:13]
	s_waitcnt vmcnt(0)
	s_waitcnt vmcnt(0)
.LBB0_544:
	s_andn2_saveexec_b64 s[10:11], s[10:11]
	s_cbranch_execz .LBB0_564
	s_mov_b64 s[10:11], exec
	buffer_wbl2 sc1
	buffer_inv sc1
	s_waitcnt lgkmcnt(0)
	s_waitcnt vmcnt(0)
	v_mbcnt_lo_u32_b32 v3, s10, 0
	v_mbcnt_hi_u32_b32 v3, s11, v3
	v_cmp_eq_u32_e32 vcc, 0, v3
	s_and_saveexec_b64 s[12:13], vcc
	s_cbranch_execz .LBB0_547
	s_bcnt1_i32_b64 s10, s[10:11]
	v_mov_b32_e32 v4, 0x1bc3000
	v_mov_b32_e32 v5, s10
	global_atomic_add v4, v4, v5, s[66:67] offset:1024 sc0

.LBB0_561:
	s_or_b64 exec, exec, s[10:11]
	s_mov_b64 s[10:11], exec
	v_mbcnt_lo_u32_b32 v2, s10, 0
	v_mbcnt_hi_u32_b32 v2, s11, v2
	v_cmp_eq_u32_e32 vcc, 0, v2
	s_waitcnt vmcnt(0)
	s_and_saveexec_b64 s[12:13], vcc
	s_cbranch_execz .LBB0_563
	s_bcnt1_i32_b64 s10, s[10:11]
	v_mov_b32_e32 v2, 0x2000
	v_mov_b32_e32 v3, s10
	global_atomic_add v2, v3, s[8:9] offset:1024

.LBB0_1568:
	s_or_b64 exec, exec, s[12:13]
	v_cvt_f32_u32_e32 v6, v4
	s_waitcnt vmcnt(0)
	v_readfirstlane_b32 s3, v5
	v_sub_u32_e32 v5, 0, v4
	v_rcp_iflag_f32_e32 v6, v6
	v_add_u32_e32 v7, s3, v3
	v_mul_f32_e32 v6, 0x4f7ffffe, v6
	v_cvt_u32_f32_e32 v6, v6
	v_mul_lo_u32 v3, v5, v6
	v_mul_hi_u32 v3, v6, v3
	v_add_u32_e32 v3, v6, v3
	v_mul_hi_u32 v3, v7, v3
	v_mul_lo_u32 v5, v3, v4
	v_sub_u32_e32 v5, v7, v5
	v_add_u32_e32 v6, 1, v3
	v_cmp_ge_u32_e32 vcc, v5, v4
	s_nop 1
	v_cndmask_b32_e32 v3, v3, v6, vcc
	v_sub_u32_e32 v6, v5, v4
	v_cndmask_b32_e32 v5, v5, v6, vcc
	v_add_u32_e32 v6, 1, v3
	v_cmp_ge_u32_e32 vcc, v5, v4
	v_add_u32_e32 v5, 1, v7
	s_nop 0
	v_cndmask_b32_e32 v3, v3, v6, vcc
	v_mul_lo_u32 v6, v4, v3
	v_add_u32_e32 v4, v6, v4
	v_cmp_ne_u32_e32 vcc, v5, v4
	s_and_saveexec_b64 s[10:11], vcc
	s_xor_b64 s[10:11], exec, s[10:11]
	s_cbranch_execz .LBB0_1582
	s_waitcnt lgkmcnt(0)
	v_mov_b32_e32 v2, 0x2000
	buffer_inv sc1
	global_load_dword v2, v2, s[8:9] offset:1024 sc1
	s_add_u32 s16, s8, 0x2400
	s_addc_u32 s17, s9, 0
	s_waitcnt vmcnt(0)
	v_cmp_eq_u32_e32 vcc, v2, v3
	s_and_saveexec_b64 s[12:13], vcc
	s_cbranch_execz .LBB0_1581
	s_add_u32 s14, s66, 0x1bc0200
	s_addc_u32 s15, s67, 0
	s_mov_b32 s3, 1
	s_mov_b64 s[18:19], 0
	v_mov_b32_e32 v2, 0
	s_branch .LBB0_1572

.LBB0_1582:
	s_andn2_saveexec_b64 s[10:11], s[10:11]
	s_cbranch_execz .LBB0_1602
	s_mov_b64 s[10:11], exec
	buffer_wbl2 sc1
	buffer_inv sc1
	s_waitcnt lgkmcnt(0)
	s_waitcnt vmcnt(0)
	v_mbcnt_lo_u32_b32 v3, s10, 0
	v_mbcnt_hi_u32_b32 v3, s11, v3
	v_cmp_eq_u32_e32 vcc, 0, v3
	s_and_saveexec_b64 s[12:13], vcc
	s_cbranch_execz .LBB0_1585
	s_bcnt1_i32_b64 s3, s[10:11]
	v_mov_b32_e32 v4, 0x1bc3000
	v_mov_b32_e32 v5, s3
	global_atomic_add v4, v4, v5, s[66:67] offset:1024 sc0

.LBB0_1599:
	s_or_b64 exec, exec, s[10:11]
	s_mov_b64 s[10:11], exec
	v_mbcnt_lo_u32_b32 v2, s10, 0
	v_mbcnt_hi_u32_b32 v2, s11, v2
	v_cmp_eq_u32_e32 vcc, 0, v2
	s_waitcnt vmcnt(0)
	s_and_saveexec_b64 s[12:13], vcc
	s_cbranch_execz .LBB0_1601
	s_bcnt1_i32_b64 s3, s[10:11]
	v_mov_b32_e32 v2, 0x2000
	v_mov_b32_e32 v3, s3
	global_atomic_add v2, v3, s[8:9] offset:1024
